# GU: next unit's SB(1,1) K-tile-1 half staged in the last K iteration; peeled S2 wait relaxed for non-first units so epilogue store acks are off the critical path
# baseline (speedup 1.0000x reference)
; #define PG8_STAGE(bufoff, gbase, voff) do { _Pragma("unroll") for (int _i = 0; _i < 2; ++_i) \
;         __builtin_amdgcn_global_load_lds((const unsigned*)((const char*)(gbase) + (voff)[_i]), (PG8_LAS unsigned*)(lds + (bufoff) + ldsw + _i * 8192), 16, 0, 0); } while (0)
; #define PG8_LDA(dst, b, h) do { _Pragma("unroll") for (int m = 0; m < 4; ++m) _Pragma("unroll") for (int k = 0; k < 2; ++k) dst[m][k] = *(const PG8_LAS bf16x8*)(lds + PG8_SA(b, h) + aoff + m * 2048 + k * 1024); } while (0)
; #define PG8_LDB(dst, b, h) do { _Pragma("unroll") for (int n = 0; n < 2; ++n) _Pragma("unroll") for (int k = 0; k < 2; ++k) dst[n][k] = *(const PG8_LAS bf16x8*)(lds + PG8_SB(b, h) + boff + n * 2048 + k * 1024); } while (0)
; #define PG8_WAIT_V(n) asm volatile("s_waitcnt vmcnt(" #n ")" ::: "memory")
; #define PG8_WAIT_L(n) asm volatile("s_waitcnt lgkmcnt(" #n ")" ::: "memory")
; #define PG8_BAR __builtin_amdgcn_s_barrier()
; #define PG8_SCHED __builtin_amdgcn_sched_barrier(0)
; template <class Epi, class Sched, bool ALIGN_EPI = false, bool SP2 = true>
; __device__ __forceinline__ void gemm_phase(PG8_LAS unsigned char* lds, const Gemm g, const Sched& S, const Epi& E) {
;     ...
;         const bool has_next = S.next(ui + 1, nxt);
;         const char* nA = has_next ? (const char*)g.A + (size_t)nxt.pm * tstepA + (size_t)nxt.pn * pnA : cA; const char* nB = has_next ? (const char*)g.Bt + (size_t)nxt.pn * tstep : cB;
;         for (int t = 0; t < nt; t += 2) {
;             const bool last = (t == nt - 2);
;             const char* a1 = cA + (size_t)(t + 1) * kstepA;
;             const char* a2 = last ? nA : cA + (size_t)(t + 2) * kstepA; const char* b2 = last ? nB : cB + (size_t)(t + 2) * kstep;
;             const char* a3 = a2 + kstepA; const char* b3 = b2 + kstep;
;             if (last && has_next) S.a_ready(nxt);
;             if constexpr (SP2) {
;             PG8_LDB(B0, 0, 0); PG8_LDB(B1, 0, 1); PG8_SCHED; PG8_LDA(At, 0, 0); PG8_STAGE(PG8_SA(1, 1), a1 + hstepA, voffA);
;             PG8_WAIT_V(8); PG8_WAIT_L(0); PG8_BAR; PG8_MMA(0, 0, At, B0); PG8_MMA(0, 1, At, B1); PG8_BAR; PG8_SCHED;
;             PG8_LDA(At, 0, 1); PG8_STAGE(PG8_SB(0, 0), b2, voffB); PG8_STAGE(PG8_SB(0, 1), b2 + hstep, voffB); PG8_STAGE(PG8_SA(0, 0), a2, voffA);
;             PG8_WAIT_V(8); PG8_WAIT_L(0); PG8_BAR; PG8_MMA(1, 0, At, B0); PG8_MMA(1, 1, At, B1); PG8_BAR; PG8_SCHED;
.LBB0_127:
	s_ashr_i32 s39, s38, 31
	s_lshl_b64 s[6:7], s[38:39], 19
	s_add_u32 s40, s54, s6
	s_addc_u32 s41, s55, s7
	s_and_b64 s[6:7], s[36:37], exec
	s_cselect_b32 s17, s41, s47
	s_cselect_b32 s39, s40, s46
	s_ashr_i32 s25, s24, 31
	s_lshl_b64 s[6:7], s[24:25], 19
	s_add_u32 s42, s26, s6
	s_addc_u32 s43, s27, s7
	s_and_b64 s[6:7], s[36:37], exec
	s_cselect_b32 s25, s43, s49
	s_cselect_b32 s59, s42, s48
	s_add_u32 s46, s46, 0x40080
	s_addc_u32 s47, s47, 0
	s_add_u32 s6, s48, 0x100
	s_addc_u32 s7, s49, 0
	s_mov_b32 s60, -2
	s_waitcnt lgkmcnt(0)
	s_add_u32 s14, s46, 0xfffc0080
	s_addc_u32 s15, s47, -1
	s_add_i32 s70, 0, 0x10000
	s_cmp_eq_u32 s60, 12
	s_cselect_b32 s51, s17, s15
	s_cselect_b32 s50, s39, s14
	v_add_u32_e32 v141, s70, v147
	s_cselect_b32 s49, s25, s7
	s_cselect_b32 s48, s59, s6
	s_add_i32 s71, 0, 0x14000
	ds_read_b128 v[152:155], v141
	ds_read_b128 v[156:159], v141 offset:1024
	ds_read_b128 v[160:163], v141 offset:2048
	ds_read_b128 v[164:167], v141 offset:3072
	v_add_u32_e32 v141, s71, v147
	ds_read_b128 v[168:171], v141
	ds_read_b128 v[172:175], v141 offset:1024
	ds_read_b128 v[176:179], v141 offset:2048
	ds_read_b128 v[180:183], v141 offset:3072
	ds_read_b128 v[184:187], v150
	ds_read_b128 v[188:191], v150 offset:1024
	ds_read_b128 v[200:203], v150 offset:2048
	ds_read_b128 v[204:207], v150 offset:3072
	ds_read_b128 v[208:211], v150 offset:4096
	ds_read_b128 v[212:215], v150 offset:5120
	ds_read_b128 v[216:219], v150 offset:6144
	ds_read_b128 v[220:223], v150 offset:7168
	v_lshl_add_u64 v[148:149], s[46:47], 0, v[136:137]
	s_add_i32 m0, s29, 0xc000
	s_nop 0
	global_load_lds_dwordx4 v[148:149], off
	v_lshl_add_u64 v[148:149], s[46:47], 0, v[138:139]
	s_add_i32 m0, s29, 0xe000
	s_nop 0
	global_load_lds_dwordx4 v[148:149], off
	s_waitcnt vmcnt(12)
	s_waitcnt lgkmcnt(0)
	s_setprio 1
	s_barrier
	v_mfma_f32_16x16x32_bf16 v[120:123], v[152:155], v[184:187], 0
	v_mfma_f32_16x16x32_bf16 v[112:115], v[160:163], v[184:187], 0
	v_mfma_f32_16x16x32_bf16 v[108:111], v[152:155], v[200:203], 0
	v_mfma_f32_16x16x32_bf16 v[96:99], v[160:163], v[200:203], 0
	v_mfma_f32_16x16x32_bf16 v[92:95], v[152:155], v[208:211], 0
	v_mfma_f32_16x16x32_bf16 v[80:83], v[160:163], v[208:211], 0
	v_mfma_f32_16x16x32_bf16 v[76:79], v[152:155], v[216:219], 0
	v_mfma_f32_16x16x32_bf16 v[64:67], v[160:163], v[216:219], 0
	v_mfma_f32_16x16x32_bf16 v[120:123], v[156:159], v[188:191], v[120:123]
	v_mfma_f32_16x16x32_bf16 v[112:115], v[164:167], v[188:191], v[112:115]
	v_mfma_f32_16x16x32_bf16 v[108:111], v[156:159], v[204:207], v[108:111]
	v_mfma_f32_16x16x32_bf16 v[96:99], v[164:167], v[204:207], v[96:99]
	v_mfma_f32_16x16x32_bf16 v[92:95], v[156:159], v[212:215], v[92:95]
	v_mfma_f32_16x16x32_bf16 v[80:83], v[164:167], v[212:215], v[80:83]
	v_mfma_f32_16x16x32_bf16 v[76:79], v[156:159], v[220:223], v[76:79]
	v_mfma_f32_16x16x32_bf16 v[64:67], v[164:167], v[220:223], v[64:67]
	v_mfma_f32_16x16x32_bf16 v[124:127], v[168:171], v[184:187], 0
	v_mfma_f32_16x16x32_bf16 v[116:119], v[176:179], v[184:187], 0
	v_mfma_f32_16x16x32_bf16 v[104:107], v[168:171], v[200:203], 0
	v_mfma_f32_16x16x32_bf16 v[100:103], v[176:179], v[200:203], 0
	v_mfma_f32_16x16x32_bf16 v[88:91], v[168:171], v[208:211], 0
	v_mfma_f32_16x16x32_bf16 v[84:87], v[176:179], v[208:211], 0
	v_mfma_f32_16x16x32_bf16 v[72:75], v[168:171], v[216:219], 0
	v_mfma_f32_16x16x32_bf16 v[68:71], v[176:179], v[216:219], 0
	v_mfma_f32_16x16x32_bf16 v[124:127], v[172:175], v[188:191], v[124:127]
	v_mfma_f32_16x16x32_bf16 v[116:119], v[180:183], v[188:191], v[116:119]
	v_mfma_f32_16x16x32_bf16 v[104:107], v[172:175], v[204:207], v[104:107]
	v_mfma_f32_16x16x32_bf16 v[100:103], v[180:183], v[204:207], v[100:103]
	v_mfma_f32_16x16x32_bf16 v[88:91], v[172:175], v[212:215], v[88:91]
	v_mfma_f32_16x16x32_bf16 v[84:87], v[180:183], v[212:215], v[84:87]
	v_mfma_f32_16x16x32_bf16 v[72:75], v[172:175], v[220:223], v[72:75]
	v_mfma_f32_16x16x32_bf16 v[68:71], v[180:183], v[220:223], v[68:71]
	s_setprio 0
	s_barrier
	s_add_i32 s14, s70, s28
	v_lshl_add_u64 v[148:149], s[48:49], 0, v[132:133]
	s_mov_b32 m0, s14
	ds_read_b128 v[184:187], v150 offset:16384
	ds_read_b128 v[188:191], v150 offset:17408
	ds_read_b128 v[200:203], v150 offset:18432
	ds_read_b128 v[204:207], v150 offset:19456
	ds_read_b128 v[208:211], v150 offset:20480
	ds_read_b128 v[212:215], v150 offset:21504
	ds_read_b128 v[216:219], v150 offset:22528
	ds_read_b128 v[220:223], v150 offset:23552
	global_load_lds_dwordx4 v[148:149], off
	s_add_i32 m0, s14, 0x2000
	v_lshl_add_u64 v[224:225], s[48:49], 0, v[128:129]
	global_load_lds_dwordx4 v[224:225], off
	v_lshl_add_u64 v[234:235], s[50:51], 0, v[130:131]
	v_lshl_add_u64 v[226:227], s[50:51], 0, v[134:135]
	s_mov_b32 m0, s29
	s_nop 0
	global_load_lds_dwordx4 v[226:227], off
	s_mov_b32 m0, s30
	s_nop 0
	global_load_lds_dwordx4 v[234:235], off
	s_cmp_eq_u32 s57, 1
	s_cbranch_scc1 .Lgu_s2_first
	s_waitcnt vmcnt(14)
	s_branch .Lgu_s2_join
; #define PG8_STAGE(bufoff, gbase, voff) do { _Pragma("unroll") for (int _i = 0; _i < 2; ++_i) \
;         __builtin_amdgcn_global_load_lds((const unsigned*)((const char*)(gbase) + (voff)[_i]), (PG8_LAS unsigned*)(lds + (bufoff) + ldsw + _i * 8192), 16, 0, 0); } while (0)
; #define PG8_LDA(dst, b, h) do { _Pragma("unroll") for (int m = 0; m < 4; ++m) _Pragma("unroll") for (int k = 0; k < 2; ++k) dst[m][k] = *(const PG8_LAS bf16x8*)(lds + PG8_SA(b, h) + aoff + m * 2048 + k * 1024); } while (0)
; #define PG8_MMA(ai, bj, At, Bt) do { __builtin_amdgcn_s_setprio(1); _Pragma("unroll") for (int m = 0; m < 4; ++m) _Pragma("unroll") for (int n = 0; n < 2; ++n) _Pragma("unroll") for (int k = 0; k < 2; ++k) \
;         acc[ai][bj][m][n] = __builtin_amdgcn_mfma_f32_16x16x32_bf16(Bt[n][k], At[m][k], acc[ai][bj][m][n], 0, 0, 0); __builtin_amdgcn_s_setprio(0); } while (0)
; #define PG8_WAIT_V(n) asm volatile("s_waitcnt vmcnt(" #n ")" ::: "memory")
; #define PG8_WAIT_L(n) asm volatile("s_waitcnt lgkmcnt(" #n ")" ::: "memory")
; #define PG8_BAR __builtin_amdgcn_s_barrier()
; #define PG8_SCHED __builtin_amdgcn_sched_barrier(0)
; template <class Epi, class Sched, bool ALIGN_EPI = false, bool SP2 = true>
; __device__ __forceinline__ void gemm_phase(PG8_LAS unsigned char* lds, const Gemm g, const Sched& S, const Epi& E) {
;     ...
;             PG8_LDA(At, 0, 1); PG8_STAGE(PG8_SB(0, 0), b2, voffB); PG8_STAGE(PG8_SB(0, 1), b2 + hstep, voffB); PG8_STAGE(PG8_SA(0, 0), a2, voffA);
;             PG8_WAIT_V(8); PG8_WAIT_L(0); PG8_BAR; PG8_MMA(1, 0, At, B0); PG8_MMA(1, 1, At, B1); PG8_BAR; PG8_SCHED;
.Lgu_s2_first:
	s_waitcnt vmcnt(6)
.Lgu_s2_join:
	s_waitcnt lgkmcnt(0)
	s_setprio 1
	s_barrier
	v_mfma_f32_16x16x32_bf16 v[60:63], v[152:155], v[184:187], 0
	v_mfma_f32_16x16x32_bf16 v[48:51], v[160:163], v[184:187], 0
	v_mfma_f32_16x16x32_bf16 v[44:47], v[152:155], v[200:203], 0
	v_mfma_f32_16x16x32_bf16 v[32:35], v[160:163], v[200:203], 0
	v_mfma_f32_16x16x32_bf16 v[28:31], v[152:155], v[208:211], 0
	v_mfma_f32_16x16x32_bf16 v[16:19], v[160:163], v[208:211], 0
	v_mfma_f32_16x16x32_bf16 v[12:15], v[152:155], v[216:219], 0
	v_mfma_f32_16x16x32_bf16 v[4:7], v[160:163], v[216:219], 0
	v_mfma_f32_16x16x32_bf16 v[60:63], v[156:159], v[188:191], v[60:63]
	v_mfma_f32_16x16x32_bf16 v[48:51], v[164:167], v[188:191], v[48:51]
	v_mfma_f32_16x16x32_bf16 v[44:47], v[156:159], v[204:207], v[44:47]
	v_mfma_f32_16x16x32_bf16 v[32:35], v[164:167], v[204:207], v[32:35]
	v_mfma_f32_16x16x32_bf16 v[28:31], v[156:159], v[212:215], v[28:31]
	v_mfma_f32_16x16x32_bf16 v[16:19], v[164:167], v[212:215], v[16:19]
	v_mfma_f32_16x16x32_bf16 v[12:15], v[156:159], v[220:223], v[12:15]
	v_mfma_f32_16x16x32_bf16 v[4:7], v[164:167], v[220:223], v[4:7]
	v_mfma_f32_16x16x32_bf16 v[56:59], v[168:171], v[184:187], 0
	v_mfma_f32_16x16x32_bf16 v[52:55], v[176:179], v[184:187], 0
	v_mfma_f32_16x16x32_bf16 v[40:43], v[168:171], v[200:203], 0
	v_mfma_f32_16x16x32_bf16 v[36:39], v[176:179], v[200:203], 0
	v_mfma_f32_16x16x32_bf16 v[24:27], v[168:171], v[208:211], 0
	v_mfma_f32_16x16x32_bf16 v[20:23], v[176:179], v[208:211], 0
	v_mfma_f32_16x16x32_bf16 v[8:11], v[168:171], v[216:219], 0
	v_mfma_f32_16x16x32_bf16 v[0:3], v[176:179], v[216:219], 0
	v_mfma_f32_16x16x32_bf16 v[56:59], v[172:175], v[188:191], v[56:59]
	v_mfma_f32_16x16x32_bf16 v[52:55], v[180:183], v[188:191], v[52:55]
	v_mfma_f32_16x16x32_bf16 v[40:43], v[172:175], v[204:207], v[40:43]
	v_mfma_f32_16x16x32_bf16 v[36:39], v[180:183], v[204:207], v[36:39]
	v_mfma_f32_16x16x32_bf16 v[24:27], v[172:175], v[212:215], v[24:27]
	v_mfma_f32_16x16x32_bf16 v[20:23], v[180:183], v[212:215], v[20:23]
	v_mfma_f32_16x16x32_bf16 v[8:11], v[172:175], v[220:223], v[8:11]
	v_mfma_f32_16x16x32_bf16 v[0:3], v[180:183], v[220:223], v[0:3]
	s_setprio 0
	s_barrier
	s_branch .Lgu_s3

; #define PG8_STAGE(bufoff, gbase, voff) do { _Pragma("unroll") for (int _i = 0; _i < 2; ++_i) \
;         __builtin_amdgcn_global_load_lds((const unsigned*)((const char*)(gbase) + (voff)[_i]), (PG8_LAS unsigned*)(lds + (bufoff) + ldsw + _i * 8192), 16, 0, 0); } while (0)
; #define PG8_LDA(dst, b, h) do { _Pragma("unroll") for (int m = 0; m < 4; ++m) _Pragma("unroll") for (int k = 0; k < 2; ++k) dst[m][k] = *(const PG8_LAS bf16x8*)(lds + PG8_SA(b, h) + aoff + m * 2048 + k * 1024); } while (0)
; #define PG8_LDB(dst, b, h) do { _Pragma("unroll") for (int n = 0; n < 2; ++n) _Pragma("unroll") for (int k = 0; k < 2; ++k) dst[n][k] = *(const PG8_LAS bf16x8*)(lds + PG8_SB(b, h) + boff + n * 2048 + k * 1024); } while (0)
; #define PG8_MMA(ai, bj, At, Bt) do { __builtin_amdgcn_s_setprio(1); _Pragma("unroll") for (int m = 0; m < 4; ++m) _Pragma("unroll") for (int n = 0; n < 2; ++n) _Pragma("unroll") for (int k = 0; k < 2; ++k) \
;         acc[ai][bj][m][n] = __builtin_amdgcn_mfma_f32_16x16x32_bf16(Bt[n][k], At[m][k], acc[ai][bj][m][n], 0, 0, 0); __builtin_amdgcn_s_setprio(0); } while (0)
; #define PG8_WAIT_V(n) asm volatile("s_waitcnt vmcnt(" #n ")" ::: "memory")
; #define PG8_WAIT_L(n) asm volatile("s_waitcnt lgkmcnt(" #n ")" ::: "memory")
; #define PG8_BAR __builtin_amdgcn_s_barrier()
; #define PG8_SCHED __builtin_amdgcn_sched_barrier(0)
;     __device__ __forceinline__ void operator()(const f32x4 (&acc)[2][2][4][2], const Unit& u, int wr, int wc, int fr, int fq) const {
;     ...
;             for (int m = 0; m < 4; ++m) sv[ai][m] = ssq[row0 + ai * HALF + m * 16];
; template <class Epi, class Sched, bool ALIGN_EPI = false, bool SP2 = true>
; __device__ __forceinline__ void gemm_phase(PG8_LAS unsigned char* lds, const Gemm g, const Sched& S, const Epi& E) {
;     ...
;             PG8_LDB(B0, 1, 0); PG8_LDB(B1, 1, 1); PG8_SCHED; PG8_LDA(At, 1, 0); PG8_STAGE(PG8_SA(0, 1), a2 + hstepA, voffA);
;             PG8_WAIT_V(8); PG8_WAIT_L(0); PG8_BAR; PG8_MMA(0, 0, At, B0); PG8_MMA(0, 1, At, B1); PG8_BAR; PG8_SCHED;
;             PG8_LDA(At, 1, 1); PG8_STAGE(PG8_SB(1, 0), b3, voffB); PG8_STAGE(PG8_SB(1, 1), b3 + hstep, voffB); PG8_STAGE(PG8_SA(1, 0), a3, voffA);
;             PG8_WAIT_V(8); PG8_WAIT_L(0); PG8_BAR; PG8_MMA(1, 0, At, B0); PG8_MMA(1, 1, At, B1); PG8_BAR; PG8_SCHED;
.Lgu_s3:
	s_add_i32 s70, 0, 0x18000
	v_add_u32_e32 v141, s70, v147
	s_add_i32 s71, 0, 0x1c000
	ds_read_b128 v[152:155], v141
	ds_read_b128 v[156:159], v141 offset:1024
	ds_read_b128 v[160:163], v141 offset:2048
	ds_read_b128 v[164:167], v141 offset:3072
	v_add_u32_e32 v141, s71, v147
	ds_read_b128 v[168:171], v141
	ds_read_b128 v[172:175], v141 offset:1024
	ds_read_b128 v[176:179], v141 offset:2048
	ds_read_b128 v[180:183], v141 offset:3072
	s_add_u32 s14, s48, 0x40000
	s_addc_u32 s15, s49, 0
	s_add_i32 m0, s28, 0x14000
	v_lshl_add_u64 v[236:237], s[14:15], 0, v[132:133]
	ds_read_b128 v[184:187], v150 offset:32768
	ds_read_b128 v[188:191], v150 offset:33792
	ds_read_b128 v[200:203], v150 offset:34816
	ds_read_b128 v[204:207], v150 offset:35840
	ds_read_b128 v[208:211], v150 offset:36864
	ds_read_b128 v[212:215], v150 offset:37888
	ds_read_b128 v[216:219], v150 offset:38912
	ds_read_b128 v[220:223], v150 offset:39936
	global_load_lds_dwordx4 v[236:237], off
	v_lshl_add_u64 v[236:237], s[14:15], 0, v[128:129]
	s_add_i32 m0, s28, 0x16000
	s_add_u32 s14, s50, 0x40000
	s_addc_u32 s15, s51, 0
	global_load_lds_dwordx4 v[236:237], off
	v_lshl_add_u64 v[236:237], s[14:15], 0, v[134:135]
	s_mov_b32 m0, s31
	s_nop 0
	global_load_lds_dwordx4 v[236:237], off
	v_lshl_add_u64 v[236:237], s[14:15], 0, v[130:131]
	s_mov_b32 m0, s34
	s_nop 0
	global_load_lds_dwordx4 v[236:237], off
	s_waitcnt vmcnt(8)
	s_waitcnt lgkmcnt(0)
	s_setprio 1
	s_barrier
	v_mfma_f32_16x16x32_bf16 v[120:123], v[152:155], v[184:187], v[120:123]
	v_mfma_f32_16x16x32_bf16 v[112:115], v[160:163], v[184:187], v[112:115]
	v_mfma_f32_16x16x32_bf16 v[108:111], v[152:155], v[200:203], v[108:111]
	v_mfma_f32_16x16x32_bf16 v[96:99], v[160:163], v[200:203], v[96:99]
	v_mfma_f32_16x16x32_bf16 v[92:95], v[152:155], v[208:211], v[92:95]
	v_mfma_f32_16x16x32_bf16 v[80:83], v[160:163], v[208:211], v[80:83]
	v_mfma_f32_16x16x32_bf16 v[76:79], v[152:155], v[216:219], v[76:79]
	v_mfma_f32_16x16x32_bf16 v[64:67], v[160:163], v[216:219], v[64:67]
	v_mfma_f32_16x16x32_bf16 v[120:123], v[156:159], v[188:191], v[120:123]
	v_mfma_f32_16x16x32_bf16 v[112:115], v[164:167], v[188:191], v[112:115]
	v_mfma_f32_16x16x32_bf16 v[108:111], v[156:159], v[204:207], v[108:111]
	v_mfma_f32_16x16x32_bf16 v[96:99], v[164:167], v[204:207], v[96:99]
	v_mfma_f32_16x16x32_bf16 v[92:95], v[156:159], v[212:215], v[92:95]
	v_mfma_f32_16x16x32_bf16 v[80:83], v[164:167], v[212:215], v[80:83]
	v_mfma_f32_16x16x32_bf16 v[76:79], v[156:159], v[220:223], v[76:79]
	v_mfma_f32_16x16x32_bf16 v[64:67], v[164:167], v[220:223], v[64:67]
	v_mfma_f32_16x16x32_bf16 v[124:127], v[168:171], v[184:187], v[124:127]
	v_mfma_f32_16x16x32_bf16 v[116:119], v[176:179], v[184:187], v[116:119]
	v_mfma_f32_16x16x32_bf16 v[104:107], v[168:171], v[200:203], v[104:107]
	v_mfma_f32_16x16x32_bf16 v[100:103], v[176:179], v[200:203], v[100:103]
	v_mfma_f32_16x16x32_bf16 v[88:91], v[168:171], v[208:211], v[88:91]
	v_mfma_f32_16x16x32_bf16 v[84:87], v[176:179], v[208:211], v[84:87]
	v_mfma_f32_16x16x32_bf16 v[72:75], v[168:171], v[216:219], v[72:75]
	v_mfma_f32_16x16x32_bf16 v[68:71], v[176:179], v[216:219], v[68:71]
	v_mfma_f32_16x16x32_bf16 v[124:127], v[172:175], v[188:191], v[124:127]
	v_mfma_f32_16x16x32_bf16 v[116:119], v[180:183], v[188:191], v[116:119]
	v_mfma_f32_16x16x32_bf16 v[104:107], v[172:175], v[204:207], v[104:107]
	v_mfma_f32_16x16x32_bf16 v[100:103], v[180:183], v[204:207], v[100:103]
	v_mfma_f32_16x16x32_bf16 v[88:91], v[172:175], v[212:215], v[88:91]
	v_mfma_f32_16x16x32_bf16 v[84:87], v[180:183], v[212:215], v[84:87]
	v_mfma_f32_16x16x32_bf16 v[72:75], v[172:175], v[220:223], v[72:75]
	v_mfma_f32_16x16x32_bf16 v[68:71], v[180:183], v[220:223], v[68:71]
	s_setprio 0
	s_barrier
	s_add_i32 s14, s70, s28
	v_lshl_add_u64 v[148:149], v[148:149], 0, s[18:19]
	s_mov_b32 m0, s14
	ds_read_b128 v[184:187], v150 offset:49152
	ds_read_b128 v[188:191], v150 offset:50176
	ds_read_b128 v[200:203], v150 offset:51200
	ds_read_b128 v[204:207], v150 offset:52224
	ds_read_b128 v[208:211], v150 offset:53248
	ds_read_b128 v[212:215], v150 offset:54272
	ds_read_b128 v[216:219], v150 offset:55296
	ds_read_b128 v[220:223], v150 offset:56320
	global_load_lds_dwordx4 v[148:149], off
	s_add_i32 m0, s14, 0x2000
	v_lshl_add_u64 v[148:149], v[224:225], 0, s[18:19]
	global_load_lds_dwordx4 v[148:149], off
	v_lshl_add_u64 v[148:149], v[226:227], 0, s[18:19]
	s_mov_b32 m0, s52
	s_nop 0
	global_load_lds_dwordx4 v[148:149], off
	v_lshl_add_u64 v[148:149], v[234:235], 0, s[18:19]
	s_mov_b32 m0, s53
	s_nop 0
	global_load_lds_dwordx4 v[148:149], off
	s_waitcnt vmcnt(6)
	s_waitcnt lgkmcnt(0)
	s_cmp_lg_u32 s60, 12
	s_cbranch_scc1 .Lgu_no_ssq_prefetch
	s_add_u32 s14, s48, 0x40080
	s_addc_u32 s15, s49, 0
	v_lshl_add_u64 v[148:149], s[14:15], 0, v[132:133]
	s_add_i32 m0, s28, 0x1c000
	s_nop 0
	global_load_lds_dwordx4 v[148:149], off
	v_lshl_add_u64 v[148:149], s[14:15], 0, v[128:129]
	s_add_i32 m0, s28, 0x1e000
	s_nop 0
	global_load_lds_dwordx4 v[148:149], off
	v_lshl_add_u32 v148, s58, 8, v145
	v_ashrrev_i32_e32 v149, 31, v148
	v_lshl_add_u64 v[148:149], v[148:149], 3, s[10:11]
	global_load_dwordx2 v[238:239], v[148:149], off
	global_load_dwordx2 v[240:241], v[148:149], off offset:128
	global_load_dwordx2 v[242:243], v[148:149], off offset:256
	global_load_dwordx2 v[244:245], v[148:149], off offset:384
	global_load_dwordx2 v[246:247], v[148:149], off offset:1024
	global_load_dwordx2 v[248:249], v[148:149], off offset:1152
	global_load_dwordx2 v[250:251], v[148:149], off offset:1280
	global_load_dwordx2 v[228:229], v[148:149], off offset:1408
